# peel69: accumulator clears removed via peeled first K-tile also in out-proj and down-proj K-loops
# speedup vs baseline: 1.0055x; 1.0055x over previous
.LBB0_577:
	s_ashr_i32 s17, s16, 31
	s_lshl_b64 s[18:19], s[16:17], 19
	s_add_u32 s18, s34, s18
	s_addc_u32 s19, s35, s19
	s_and_b64 s[20:21], s[0:1], exec
	s_cselect_b32 s17, s19, s25
	s_cselect_b32 s48, s18, s24
	s_ashr_i32 s15, s14, 31
	s_lshl_b64 s[20:21], s[14:15], 19
	s_add_u32 s20, s36, s20
	s_addc_u32 s21, s37, s21
	s_and_b64 s[26:27], s[0:1], exec
	s_cselect_b32 s15, s21, s23
	s_cselect_b32 s49, s20, s22
	s_add_u32 s50, s22, 0x100
	s_addc_u32 s51, s23, 0
	s_add_u32 s22, s24, 0x40080
	v_mov_b32_e32 v0, 0
	s_addc_u32 s23, s25, 0
	s_mov_b32 s52, -2
	s_add_u32 s24, s22, 0xfffc0080
	s_addc_u32 s25, s23, -1
	s_add_i32 s53, 0, 0x10000
	s_cmp_eq_u32 s52, 12
	s_cselect_b32 s27, s17, s25
	s_cselect_b32 s26, s48, s24
	s_cselect_b32 s25, s15, s51
	s_cselect_b32 s24, s49, s50
	s_add_i32 s56, 0, 0x14000
	v_add_u32_e32 v140, s53, v163
	v_add_u32_e32 v166, s56, v163
	ds_read_b128 v[128:131], v140
	ds_read_b128 v[132:135], v140 offset:1024
	ds_read_b128 v[136:139], v140 offset:2048
	ds_read_b128 v[140:143], v140 offset:3072
	ds_read_b128 v[154:157], v166
	ds_read_b128 v[158:161], v166 offset:1024
	ds_read_b128 v[170:173], v166 offset:2048
	ds_read_b128 v[174:177], v166 offset:3072
	v_lshl_add_u64 v[166:167], s[22:23], 0, v[152:153]
	s_add_i32 m0, s29, 0xc000
	ds_read_b128 v[178:181], v165
	ds_read_b128 v[182:185], v165 offset:1024
	ds_read_b128 v[186:189], v165 offset:2048
	ds_read_b128 v[190:193], v165 offset:3072
	ds_read_b128 v[194:197], v165 offset:4096
	ds_read_b128 v[198:201], v165 offset:5120
	ds_read_b128 v[202:205], v165 offset:6144
	ds_read_b128 v[212:215], v165 offset:7168
	global_load_lds_dwordx4 v[166:167], off
	v_lshl_add_u64 v[166:167], s[22:23], 0, v[150:151]
	s_add_i32 m0, s29, 0xe000
	s_nop 0
	global_load_lds_dwordx4 v[166:167], off
	s_waitcnt vmcnt(8)
	s_waitcnt lgkmcnt(0)
	s_barrier
	s_waitcnt lgkmcnt(0)
	v_mfma_f32_16x16x32_bf16 v[124:127], v[128:131], v[178:181], 0
	v_mfma_f32_16x16x32_bf16 v[120:123], v[136:139], v[178:181], 0
	v_mfma_f32_16x16x32_bf16 v[112:115], v[128:131], v[186:189], 0
	v_mfma_f32_16x16x32_bf16 v[104:107], v[136:139], v[186:189], 0
	v_mfma_f32_16x16x32_bf16 v[92:95], v[128:131], v[194:197], 0
	v_mfma_f32_16x16x32_bf16 v[88:91], v[136:139], v[194:197], 0
	v_mfma_f32_16x16x32_bf16 v[76:79], v[128:131], v[202:205], 0
	v_mfma_f32_16x16x32_bf16 v[72:75], v[136:139], v[202:205], 0
	v_mfma_f32_16x16x32_bf16 v[124:127], v[132:135], v[182:185], v[124:127]
	v_mfma_f32_16x16x32_bf16 v[120:123], v[140:143], v[182:185], v[120:123]
	v_mfma_f32_16x16x32_bf16 v[112:115], v[132:135], v[190:193], v[112:115]
	v_mfma_f32_16x16x32_bf16 v[104:107], v[140:143], v[190:193], v[104:107]
	v_mfma_f32_16x16x32_bf16 v[92:95], v[132:135], v[198:201], v[92:95]
	v_mfma_f32_16x16x32_bf16 v[88:91], v[140:143], v[198:201], v[88:91]
	v_mfma_f32_16x16x32_bf16 v[76:79], v[132:135], v[212:215], v[76:79]
	v_mfma_f32_16x16x32_bf16 v[72:75], v[140:143], v[212:215], v[72:75]
	v_mfma_f32_16x16x32_bf16 v[116:119], v[154:157], v[178:181], 0
	v_mfma_f32_16x16x32_bf16 v[108:111], v[170:173], v[178:181], 0
	v_mfma_f32_16x16x32_bf16 v[100:103], v[154:157], v[186:189], 0
	v_mfma_f32_16x16x32_bf16 v[96:99], v[170:173], v[186:189], 0
	v_mfma_f32_16x16x32_bf16 v[84:87], v[154:157], v[194:197], 0
	v_mfma_f32_16x16x32_bf16 v[80:83], v[170:173], v[194:197], 0
	v_mfma_f32_16x16x32_bf16 v[68:71], v[154:157], v[202:205], 0
	v_mfma_f32_16x16x32_bf16 v[64:67], v[170:173], v[202:205], 0
	v_mfma_f32_16x16x32_bf16 v[116:119], v[158:161], v[182:185], v[116:119]
	v_mfma_f32_16x16x32_bf16 v[108:111], v[174:177], v[182:185], v[108:111]
	v_mfma_f32_16x16x32_bf16 v[100:103], v[158:161], v[190:193], v[100:103]
	v_mfma_f32_16x16x32_bf16 v[96:99], v[174:177], v[190:193], v[96:99]
	v_mfma_f32_16x16x32_bf16 v[84:87], v[158:161], v[198:201], v[84:87]
	v_mfma_f32_16x16x32_bf16 v[80:83], v[174:177], v[198:201], v[80:83]
	v_mfma_f32_16x16x32_bf16 v[68:71], v[158:161], v[212:215], v[68:71]
	v_mfma_f32_16x16x32_bf16 v[64:67], v[174:177], v[212:215], v[64:67]
	s_barrier
	s_add_i32 s53, s53, s28
	v_lshl_add_u64 v[166:167], s[24:25], 0, v[168:169]
	s_mov_b32 m0, s53
	ds_read_b128 v[178:181], v165 offset:16384
	ds_read_b128 v[182:185], v165 offset:17408
	ds_read_b128 v[186:189], v165 offset:18432
	ds_read_b128 v[190:193], v165 offset:19456
	ds_read_b128 v[194:197], v165 offset:20480
	ds_read_b128 v[198:201], v165 offset:21504
	ds_read_b128 v[202:205], v165 offset:22528
	ds_read_b128 v[212:215], v165 offset:23552
	global_load_lds_dwordx4 v[166:167], off
	s_add_i32 m0, s53, 0x2000
	s_add_u32 s54, s24, 0x40000
	v_lshl_add_u64 v[216:217], s[24:25], 0, v[144:145]
	s_addc_u32 s55, s25, 0
	s_add_i32 s53, s56, s28
	global_load_lds_dwordx4 v[216:217], off
	v_lshl_add_u64 v[220:221], s[54:55], 0, v[168:169]
	s_mov_b32 m0, s53
	v_lshl_add_u64 v[222:223], s[26:27], 0, v[146:147]
	global_load_lds_dwordx4 v[220:221], off
	v_lshl_add_u64 v[220:221], s[54:55], 0, v[144:145]
	s_add_i32 m0, s53, 0x2000
	s_nop 0
	global_load_lds_dwordx4 v[220:221], off
	v_lshl_add_u64 v[220:221], s[26:27], 0, v[148:149]
	s_mov_b32 m0, s29
	s_nop 0
	global_load_lds_dwordx4 v[220:221], off
	s_mov_b32 m0, s30
	s_nop 0
	global_load_lds_dwordx4 v[222:223], off
	s_waitcnt vmcnt(8)
	s_waitcnt lgkmcnt(0)
	s_barrier
	s_waitcnt lgkmcnt(0)
	v_mfma_f32_16x16x32_bf16 v[60:63], v[128:131], v[178:181], 0
	v_mfma_f32_16x16x32_bf16 v[56:59], v[136:139], v[178:181], 0
	v_mfma_f32_16x16x32_bf16 v[44:47], v[128:131], v[186:189], 0
	v_mfma_f32_16x16x32_bf16 v[40:43], v[136:139], v[186:189], 0
	v_mfma_f32_16x16x32_bf16 v[28:31], v[128:131], v[194:197], 0
	v_mfma_f32_16x16x32_bf16 v[24:27], v[136:139], v[194:197], 0
	v_mfma_f32_16x16x32_bf16 v[12:15], v[128:131], v[202:205], 0
	v_mfma_f32_16x16x32_bf16 v[8:11], v[136:139], v[202:205], 0
	v_mfma_f32_16x16x32_bf16 v[60:63], v[132:135], v[182:185], v[60:63]
	v_mfma_f32_16x16x32_bf16 v[56:59], v[140:143], v[182:185], v[56:59]
	v_mfma_f32_16x16x32_bf16 v[44:47], v[132:135], v[190:193], v[44:47]
	v_mfma_f32_16x16x32_bf16 v[40:43], v[140:143], v[190:193], v[40:43]
	v_mfma_f32_16x16x32_bf16 v[28:31], v[132:135], v[198:201], v[28:31]
	v_mfma_f32_16x16x32_bf16 v[24:27], v[140:143], v[198:201], v[24:27]
	v_mfma_f32_16x16x32_bf16 v[12:15], v[132:135], v[212:215], v[12:15]
	v_mfma_f32_16x16x32_bf16 v[8:11], v[140:143], v[212:215], v[8:11]
	v_mfma_f32_16x16x32_bf16 v[52:55], v[154:157], v[178:181], 0
	v_mfma_f32_16x16x32_bf16 v[48:51], v[170:173], v[178:181], 0
	v_mfma_f32_16x16x32_bf16 v[36:39], v[154:157], v[186:189], 0
	v_mfma_f32_16x16x32_bf16 v[32:35], v[170:173], v[186:189], 0
	v_mfma_f32_16x16x32_bf16 v[20:23], v[154:157], v[194:197], 0
	v_mfma_f32_16x16x32_bf16 v[16:19], v[170:173], v[194:197], 0
	v_mfma_f32_16x16x32_bf16 v[4:7], v[154:157], v[202:205], 0
	v_mfma_f32_16x16x32_bf16 v[0:3], v[170:173], v[202:205], 0
	v_mfma_f32_16x16x32_bf16 v[52:55], v[158:161], v[182:185], v[52:55]
	v_mfma_f32_16x16x32_bf16 v[48:51], v[174:177], v[182:185], v[48:51]
	v_mfma_f32_16x16x32_bf16 v[36:39], v[158:161], v[190:193], v[36:39]
	v_mfma_f32_16x16x32_bf16 v[32:35], v[174:177], v[190:193], v[32:35]
	v_mfma_f32_16x16x32_bf16 v[20:23], v[158:161], v[198:201], v[20:23]
	v_mfma_f32_16x16x32_bf16 v[16:19], v[174:177], v[198:201], v[16:19]
	v_mfma_f32_16x16x32_bf16 v[4:7], v[158:161], v[212:215], v[4:7]
	v_mfma_f32_16x16x32_bf16 v[0:3], v[174:177], v[212:215], v[0:3]
	s_barrier
	s_branch .Lpeel_p6a

.Lpeel_p6a:
	s_add_i32 s53, 0, 0x18000
	s_add_i32 s54, 0, 0x1c000
	v_add_u32_e32 v140, s53, v163
	v_add_u32_e32 v174, s54, v163
	ds_read_b128 v[128:131], v140
	ds_read_b128 v[132:135], v140 offset:1024
	ds_read_b128 v[136:139], v140 offset:2048
	ds_read_b128 v[140:143], v140 offset:3072
	ds_read_b128 v[154:157], v174
	ds_read_b128 v[158:161], v174 offset:1024
	ds_read_b128 v[170:173], v174 offset:2048
	ds_read_b128 v[174:177], v174 offset:3072
	s_add_u32 s26, s26, 0x40000
	s_addc_u32 s27, s27, 0
	s_mov_b32 m0, s31
	v_lshl_add_u64 v[224:225], s[26:27], 0, v[148:149]
	ds_read_b128 v[178:181], v165 offset:32768
	ds_read_b128 v[182:185], v165 offset:33792
	ds_read_b128 v[186:189], v165 offset:34816
	ds_read_b128 v[190:193], v165 offset:35840
	ds_read_b128 v[194:197], v165 offset:36864
	ds_read_b128 v[198:201], v165 offset:37888
	ds_read_b128 v[202:205], v165 offset:38912
	ds_read_b128 v[212:215], v165 offset:39936
	global_load_lds_dwordx4 v[224:225], off
	v_lshl_add_u64 v[224:225], s[26:27], 0, v[146:147]
	s_mov_b32 m0, s40
	s_nop 0
	global_load_lds_dwordx4 v[224:225], off
	s_waitcnt vmcnt(8)
	s_waitcnt lgkmcnt(0)
	s_barrier
	s_waitcnt lgkmcnt(0)
	v_mfma_f32_16x16x32_bf16 v[124:127], v[128:131], v[178:181], v[124:127]
	v_mfma_f32_16x16x32_bf16 v[120:123], v[136:139], v[178:181], v[120:123]
	v_mfma_f32_16x16x32_bf16 v[112:115], v[128:131], v[186:189], v[112:115]
	v_mfma_f32_16x16x32_bf16 v[104:107], v[136:139], v[186:189], v[104:107]
	v_mfma_f32_16x16x32_bf16 v[92:95], v[128:131], v[194:197], v[92:95]
	v_mfma_f32_16x16x32_bf16 v[88:91], v[136:139], v[194:197], v[88:91]
	v_mfma_f32_16x16x32_bf16 v[76:79], v[128:131], v[202:205], v[76:79]
	v_mfma_f32_16x16x32_bf16 v[72:75], v[136:139], v[202:205], v[72:75]
	v_mfma_f32_16x16x32_bf16 v[124:127], v[132:135], v[182:185], v[124:127]
	v_mfma_f32_16x16x32_bf16 v[120:123], v[140:143], v[182:185], v[120:123]
	v_mfma_f32_16x16x32_bf16 v[112:115], v[132:135], v[190:193], v[112:115]
	v_mfma_f32_16x16x32_bf16 v[104:107], v[140:143], v[190:193], v[104:107]
	v_mfma_f32_16x16x32_bf16 v[92:95], v[132:135], v[198:201], v[92:95]
	v_mfma_f32_16x16x32_bf16 v[88:91], v[140:143], v[198:201], v[88:91]
	v_mfma_f32_16x16x32_bf16 v[76:79], v[132:135], v[212:215], v[76:79]
	v_mfma_f32_16x16x32_bf16 v[72:75], v[140:143], v[212:215], v[72:75]
	v_mfma_f32_16x16x32_bf16 v[116:119], v[154:157], v[178:181], v[116:119]
	v_mfma_f32_16x16x32_bf16 v[108:111], v[170:173], v[178:181], v[108:111]
	v_mfma_f32_16x16x32_bf16 v[100:103], v[154:157], v[186:189], v[100:103]
	v_mfma_f32_16x16x32_bf16 v[96:99], v[170:173], v[186:189], v[96:99]
	v_mfma_f32_16x16x32_bf16 v[84:87], v[154:157], v[194:197], v[84:87]
	v_mfma_f32_16x16x32_bf16 v[80:83], v[170:173], v[194:197], v[80:83]
	v_mfma_f32_16x16x32_bf16 v[68:71], v[154:157], v[202:205], v[68:71]
	v_mfma_f32_16x16x32_bf16 v[64:67], v[170:173], v[202:205], v[64:67]
	v_mfma_f32_16x16x32_bf16 v[116:119], v[158:161], v[182:185], v[116:119]
	v_mfma_f32_16x16x32_bf16 v[108:111], v[174:177], v[182:185], v[108:111]
	v_mfma_f32_16x16x32_bf16 v[100:103], v[158:161], v[190:193], v[100:103]
	v_mfma_f32_16x16x32_bf16 v[96:99], v[174:177], v[190:193], v[96:99]
	v_mfma_f32_16x16x32_bf16 v[84:87], v[158:161], v[198:201], v[84:87]
	v_mfma_f32_16x16x32_bf16 v[80:83], v[174:177], v[198:201], v[80:83]
	v_mfma_f32_16x16x32_bf16 v[68:71], v[158:161], v[212:215], v[68:71]
	v_mfma_f32_16x16x32_bf16 v[64:67], v[174:177], v[212:215], v[64:67]
	s_barrier
	s_add_i32 s26, s53, s28
	v_lshl_add_u64 v[166:167], v[166:167], 0, s[74:75]
	s_mov_b32 m0, s26
	ds_read_b128 v[178:181], v165 offset:49152
	ds_read_b128 v[182:185], v165 offset:50176
	ds_read_b128 v[186:189], v165 offset:51200
	ds_read_b128 v[190:193], v165 offset:52224
	ds_read_b128 v[194:197], v165 offset:53248
	ds_read_b128 v[198:201], v165 offset:54272
	ds_read_b128 v[202:205], v165 offset:55296
	ds_read_b128 v[212:215], v165 offset:56320
	global_load_lds_dwordx4 v[166:167], off
	s_add_i32 m0, s26, 0x2000
	s_add_u32 s24, s24, 0x40080
	v_lshl_add_u64 v[166:167], v[216:217], 0, s[74:75]
	s_addc_u32 s25, s25, 0
	s_add_i32 s26, s54, s28
	global_load_lds_dwordx4 v[166:167], off
	v_lshl_add_u64 v[166:167], s[24:25], 0, v[168:169]
	s_mov_b32 m0, s26
	s_nop 0
	global_load_lds_dwordx4 v[166:167], off
	v_lshl_add_u64 v[166:167], s[24:25], 0, v[144:145]
	s_add_i32 m0, s26, 0x2000
	s_nop 0
	global_load_lds_dwordx4 v[166:167], off
	v_lshl_add_u64 v[166:167], v[220:221], 0, s[74:75]
	s_mov_b32 m0, s43
	s_nop 0
	global_load_lds_dwordx4 v[166:167], off
	v_lshl_add_u64 v[166:167], v[222:223], 0, s[74:75]
	s_mov_b32 m0, s44
	s_nop 0
	global_load_lds_dwordx4 v[166:167], off
	s_waitcnt vmcnt(8)
	s_waitcnt lgkmcnt(0)
	s_barrier
	s_waitcnt lgkmcnt(0)
	v_mfma_f32_16x16x32_bf16 v[60:63], v[128:131], v[178:181], v[60:63]
	v_mfma_f32_16x16x32_bf16 v[56:59], v[136:139], v[178:181], v[56:59]
	v_mfma_f32_16x16x32_bf16 v[44:47], v[128:131], v[186:189], v[44:47]
	v_mfma_f32_16x16x32_bf16 v[40:43], v[136:139], v[186:189], v[40:43]
	v_mfma_f32_16x16x32_bf16 v[28:31], v[128:131], v[194:197], v[28:31]
	v_mfma_f32_16x16x32_bf16 v[24:27], v[136:139], v[194:197], v[24:27]
	v_mfma_f32_16x16x32_bf16 v[12:15], v[128:131], v[202:205], v[12:15]
	v_mfma_f32_16x16x32_bf16 v[8:11], v[136:139], v[202:205], v[8:11]
	v_mfma_f32_16x16x32_bf16 v[60:63], v[132:135], v[182:185], v[60:63]
	v_mfma_f32_16x16x32_bf16 v[56:59], v[140:143], v[182:185], v[56:59]
	v_mfma_f32_16x16x32_bf16 v[44:47], v[132:135], v[190:193], v[44:47]
	v_mfma_f32_16x16x32_bf16 v[40:43], v[140:143], v[190:193], v[40:43]
	v_mfma_f32_16x16x32_bf16 v[28:31], v[132:135], v[198:201], v[28:31]
	v_mfma_f32_16x16x32_bf16 v[24:27], v[140:143], v[198:201], v[24:27]
	v_mfma_f32_16x16x32_bf16 v[12:15], v[132:135], v[212:215], v[12:15]
	v_mfma_f32_16x16x32_bf16 v[8:11], v[140:143], v[212:215], v[8:11]
	v_mfma_f32_16x16x32_bf16 v[52:55], v[154:157], v[178:181], v[52:55]
	v_mfma_f32_16x16x32_bf16 v[48:51], v[170:173], v[178:181], v[48:51]
	v_mfma_f32_16x16x32_bf16 v[36:39], v[154:157], v[186:189], v[36:39]
	v_mfma_f32_16x16x32_bf16 v[32:35], v[170:173], v[186:189], v[32:35]
	v_mfma_f32_16x16x32_bf16 v[20:23], v[154:157], v[194:197], v[20:23]
	v_mfma_f32_16x16x32_bf16 v[16:19], v[170:173], v[194:197], v[16:19]
	v_mfma_f32_16x16x32_bf16 v[4:7], v[154:157], v[202:205], v[4:7]
	v_mfma_f32_16x16x32_bf16 v[0:3], v[170:173], v[202:205], v[0:3]
	v_mfma_f32_16x16x32_bf16 v[52:55], v[158:161], v[182:185], v[52:55]
	v_mfma_f32_16x16x32_bf16 v[48:51], v[174:177], v[182:185], v[48:51]
	v_mfma_f32_16x16x32_bf16 v[36:39], v[158:161], v[190:193], v[36:39]
	v_mfma_f32_16x16x32_bf16 v[32:35], v[174:177], v[190:193], v[32:35]
	v_mfma_f32_16x16x32_bf16 v[20:23], v[158:161], v[198:201], v[20:23]
	v_mfma_f32_16x16x32_bf16 v[16:19], v[174:177], v[198:201], v[16:19]
	v_mfma_f32_16x16x32_bf16 v[4:7], v[158:161], v[212:215], v[4:7]
	v_mfma_f32_16x16x32_bf16 v[0:3], v[174:177], v[212:215], v[0:3]
	s_barrier
	s_add_i32 s52, s52, 2
	s_add_u32 s50, s50, 0x100
	s_addc_u32 s51, s51, 0
	s_add_u32 s22, s22, 0x100
	s_addc_u32 s23, s23, 0
	s_cmp_gt_u32 s52, 13
	s_cbranch_scc0 .LBB0_578
	v_readlane_b32 s52, v254, 51
	s_and_b64 vcc, exec, s[12:13]
	v_readlane_b32 s53, v254, 52
	s_cbranch_vccz .LBB0_581
	s_barrier

.LBB0_654:
	s_ashr_i32 s13, s12, 31
	s_lshl_b64 s[14:15], s[12:13], 19
	s_add_u32 s14, s34, s14
	s_addc_u32 s15, s35, s15
	s_and_b64 s[16:17], s[0:1], exec
	s_cselect_b32 s13, s15, s21
	s_cselect_b32 s42, s14, s20
	s_ashr_i32 s11, s10, 31
	s_lshl_b64 s[16:17], s[10:11], 19
	s_add_u32 s16, s36, s16
	s_addc_u32 s17, s37, s17
	s_and_b64 s[22:23], s[0:1], exec
	s_cselect_b32 s11, s17, s19
	s_cselect_b32 s43, s16, s18
	s_add_u32 s44, s18, 0x100
	s_addc_u32 s45, s19, 0
	s_add_u32 s18, s20, 0x40080
	v_mov_b32_e32 v0, 0
	s_addc_u32 s19, s21, 0
	s_mov_b32 s46, -2
	s_add_u32 s20, s18, 0xfffc0080
	s_addc_u32 s21, s19, -1
	s_add_i32 s47, 0, 0x10000
	s_cmp_eq_u32 s46, 12
	s_cselect_b32 s23, s13, s21
	s_cselect_b32 s22, s42, s20
	s_cselect_b32 s21, s11, s45
	s_cselect_b32 s20, s43, s44
	s_add_i32 s50, 0, 0x14000
	v_add_u32_e32 v76, s47, v159
	v_add_u32_e32 v166, s50, v159
	ds_read_b128 v[64:67], v76
	ds_read_b128 v[68:71], v76 offset:1024
	ds_read_b128 v[72:75], v76 offset:2048
	ds_read_b128 v[76:79], v76 offset:3072
	ds_read_b128 v[154:157], v166
	ds_read_b128 v[162:165], v166 offset:1024
	ds_read_b128 v[170:173], v166 offset:2048
	ds_read_b128 v[174:177], v166 offset:3072
	v_lshl_add_u64 v[166:167], s[18:19], 0, v[152:153]
	s_add_i32 m0, s25, 0xc000
	ds_read_b128 v[178:181], v161
	ds_read_b128 v[182:185], v161 offset:1024
	ds_read_b128 v[186:189], v161 offset:2048
	ds_read_b128 v[190:193], v161 offset:3072
	ds_read_b128 v[194:197], v161 offset:4096
	ds_read_b128 v[198:201], v161 offset:5120
	ds_read_b128 v[202:205], v161 offset:6144
	ds_read_b128 v[212:215], v161 offset:7168
	global_load_lds_dwordx4 v[166:167], off
	v_lshl_add_u64 v[166:167], s[18:19], 0, v[150:151]
	s_add_i32 m0, s25, 0xe000
	s_nop 0
	global_load_lds_dwordx4 v[166:167], off
	s_waitcnt vmcnt(8)
	s_waitcnt lgkmcnt(0)
	s_barrier
	s_waitcnt lgkmcnt(0)
	v_mfma_f32_16x16x32_bf16 v[140:143], v[64:67], v[178:181], 0
	v_mfma_f32_16x16x32_bf16 v[136:139], v[72:75], v[178:181], 0
	v_mfma_f32_16x16x32_bf16 v[132:135], v[64:67], v[186:189], 0
	v_mfma_f32_16x16x32_bf16 v[128:131], v[72:75], v[186:189], 0
	v_mfma_f32_16x16x32_bf16 v[108:111], v[64:67], v[194:197], 0
	v_mfma_f32_16x16x32_bf16 v[104:107], v[72:75], v[194:197], 0
	v_mfma_f32_16x16x32_bf16 v[100:103], v[64:67], v[202:205], 0
	v_mfma_f32_16x16x32_bf16 v[96:99], v[72:75], v[202:205], 0
	v_mfma_f32_16x16x32_bf16 v[140:143], v[68:71], v[182:185], v[140:143]
	v_mfma_f32_16x16x32_bf16 v[136:139], v[76:79], v[182:185], v[136:139]
	v_mfma_f32_16x16x32_bf16 v[132:135], v[68:71], v[190:193], v[132:135]
	v_mfma_f32_16x16x32_bf16 v[128:131], v[76:79], v[190:193], v[128:131]
	v_mfma_f32_16x16x32_bf16 v[108:111], v[68:71], v[198:201], v[108:111]
	v_mfma_f32_16x16x32_bf16 v[104:107], v[76:79], v[198:201], v[104:107]
	v_mfma_f32_16x16x32_bf16 v[100:103], v[68:71], v[212:215], v[100:103]
	v_mfma_f32_16x16x32_bf16 v[96:99], v[76:79], v[212:215], v[96:99]
	v_mfma_f32_16x16x32_bf16 v[124:127], v[154:157], v[178:181], 0
	v_mfma_f32_16x16x32_bf16 v[120:123], v[170:173], v[178:181], 0
	v_mfma_f32_16x16x32_bf16 v[116:119], v[154:157], v[186:189], 0
	v_mfma_f32_16x16x32_bf16 v[112:115], v[170:173], v[186:189], 0
	v_mfma_f32_16x16x32_bf16 v[92:95], v[154:157], v[194:197], 0
	v_mfma_f32_16x16x32_bf16 v[88:91], v[170:173], v[194:197], 0
	v_mfma_f32_16x16x32_bf16 v[84:87], v[154:157], v[202:205], 0
	v_mfma_f32_16x16x32_bf16 v[80:83], v[170:173], v[202:205], 0
	v_mfma_f32_16x16x32_bf16 v[124:127], v[162:165], v[182:185], v[124:127]
	v_mfma_f32_16x16x32_bf16 v[120:123], v[174:177], v[182:185], v[120:123]
	v_mfma_f32_16x16x32_bf16 v[116:119], v[162:165], v[190:193], v[116:119]
	v_mfma_f32_16x16x32_bf16 v[112:115], v[174:177], v[190:193], v[112:115]
	v_mfma_f32_16x16x32_bf16 v[92:95], v[162:165], v[198:201], v[92:95]
	v_mfma_f32_16x16x32_bf16 v[88:91], v[174:177], v[198:201], v[88:91]
	v_mfma_f32_16x16x32_bf16 v[84:87], v[162:165], v[212:215], v[84:87]
	v_mfma_f32_16x16x32_bf16 v[80:83], v[174:177], v[212:215], v[80:83]
	s_barrier
	s_add_i32 s47, s47, s24
	v_lshl_add_u64 v[166:167], s[20:21], 0, v[168:169]
	s_mov_b32 m0, s47
	ds_read_b128 v[178:181], v161 offset:16384
	ds_read_b128 v[182:185], v161 offset:17408
	ds_read_b128 v[186:189], v161 offset:18432
	ds_read_b128 v[190:193], v161 offset:19456
	ds_read_b128 v[194:197], v161 offset:20480
	ds_read_b128 v[198:201], v161 offset:21504
	ds_read_b128 v[202:205], v161 offset:22528
	ds_read_b128 v[212:215], v161 offset:23552
	global_load_lds_dwordx4 v[166:167], off
	s_add_i32 m0, s47, 0x2000
	s_add_u32 s48, s20, 0x40000
	v_lshl_add_u64 v[216:217], s[20:21], 0, v[144:145]
	s_addc_u32 s49, s21, 0
	s_add_i32 s47, s50, s24
	global_load_lds_dwordx4 v[216:217], off
	v_lshl_add_u64 v[218:219], s[48:49], 0, v[168:169]
	s_mov_b32 m0, s47
	v_lshl_add_u64 v[220:221], s[22:23], 0, v[146:147]
	global_load_lds_dwordx4 v[218:219], off
	v_lshl_add_u64 v[218:219], s[48:49], 0, v[144:145]
	s_add_i32 m0, s47, 0x2000
	s_nop 0
	global_load_lds_dwordx4 v[218:219], off
	v_lshl_add_u64 v[218:219], s[22:23], 0, v[148:149]
	s_mov_b32 m0, s25
	s_nop 0
	global_load_lds_dwordx4 v[218:219], off
	s_mov_b32 m0, s26
	s_nop 0
	global_load_lds_dwordx4 v[220:221], off
	s_waitcnt vmcnt(8)
	s_waitcnt lgkmcnt(0)
	s_barrier
	s_waitcnt lgkmcnt(0)
	v_mfma_f32_16x16x32_bf16 v[60:63], v[64:67], v[178:181], 0
	v_mfma_f32_16x16x32_bf16 v[56:59], v[72:75], v[178:181], 0
	v_mfma_f32_16x16x32_bf16 v[52:55], v[64:67], v[186:189], 0
	v_mfma_f32_16x16x32_bf16 v[48:51], v[72:75], v[186:189], 0
	v_mfma_f32_16x16x32_bf16 v[28:31], v[64:67], v[194:197], 0
	v_mfma_f32_16x16x32_bf16 v[24:27], v[72:75], v[194:197], 0
	v_mfma_f32_16x16x32_bf16 v[20:23], v[64:67], v[202:205], 0
	v_mfma_f32_16x16x32_bf16 v[16:19], v[72:75], v[202:205], 0
	v_mfma_f32_16x16x32_bf16 v[60:63], v[68:71], v[182:185], v[60:63]
	v_mfma_f32_16x16x32_bf16 v[56:59], v[76:79], v[182:185], v[56:59]
	v_mfma_f32_16x16x32_bf16 v[52:55], v[68:71], v[190:193], v[52:55]
	v_mfma_f32_16x16x32_bf16 v[48:51], v[76:79], v[190:193], v[48:51]
	v_mfma_f32_16x16x32_bf16 v[28:31], v[68:71], v[198:201], v[28:31]
	v_mfma_f32_16x16x32_bf16 v[24:27], v[76:79], v[198:201], v[24:27]
	v_mfma_f32_16x16x32_bf16 v[20:23], v[68:71], v[212:215], v[20:23]
	v_mfma_f32_16x16x32_bf16 v[16:19], v[76:79], v[212:215], v[16:19]
	v_mfma_f32_16x16x32_bf16 v[44:47], v[154:157], v[178:181], 0
	v_mfma_f32_16x16x32_bf16 v[40:43], v[170:173], v[178:181], 0
	v_mfma_f32_16x16x32_bf16 v[36:39], v[154:157], v[186:189], 0
	v_mfma_f32_16x16x32_bf16 v[32:35], v[170:173], v[186:189], 0
	v_mfma_f32_16x16x32_bf16 v[12:15], v[154:157], v[194:197], 0
	v_mfma_f32_16x16x32_bf16 v[8:11], v[170:173], v[194:197], 0
	v_mfma_f32_16x16x32_bf16 v[4:7], v[154:157], v[202:205], 0
	v_mfma_f32_16x16x32_bf16 v[0:3], v[170:173], v[202:205], 0
	v_mfma_f32_16x16x32_bf16 v[44:47], v[162:165], v[182:185], v[44:47]
	v_mfma_f32_16x16x32_bf16 v[40:43], v[174:177], v[182:185], v[40:43]
	v_mfma_f32_16x16x32_bf16 v[36:39], v[162:165], v[190:193], v[36:39]
	v_mfma_f32_16x16x32_bf16 v[32:35], v[174:177], v[190:193], v[32:35]
	v_mfma_f32_16x16x32_bf16 v[12:15], v[162:165], v[198:201], v[12:15]
	v_mfma_f32_16x16x32_bf16 v[8:11], v[174:177], v[198:201], v[8:11]
	v_mfma_f32_16x16x32_bf16 v[4:7], v[162:165], v[212:215], v[4:7]
	v_mfma_f32_16x16x32_bf16 v[0:3], v[174:177], v[212:215], v[0:3]
	s_barrier
	s_branch .Lpeel_p6b

.Lpeel_p6b:
	s_add_i32 s47, 0, 0x18000
	s_add_i32 s48, 0, 0x1c000
	v_add_u32_e32 v76, s47, v159
	v_add_u32_e32 v174, s48, v159
	ds_read_b128 v[64:67], v76
	ds_read_b128 v[68:71], v76 offset:1024
	ds_read_b128 v[72:75], v76 offset:2048
	ds_read_b128 v[76:79], v76 offset:3072
	ds_read_b128 v[154:157], v174
	ds_read_b128 v[162:165], v174 offset:1024
	ds_read_b128 v[170:173], v174 offset:2048
	ds_read_b128 v[174:177], v174 offset:3072
	s_add_u32 s22, s22, 0x40000
	s_addc_u32 s23, s23, 0
	s_mov_b32 m0, s27
	v_lshl_add_u64 v[222:223], s[22:23], 0, v[148:149]
	ds_read_b128 v[178:181], v161 offset:32768
	ds_read_b128 v[182:185], v161 offset:33792
	ds_read_b128 v[186:189], v161 offset:34816
	ds_read_b128 v[190:193], v161 offset:35840
	ds_read_b128 v[194:197], v161 offset:36864
	ds_read_b128 v[198:201], v161 offset:37888
	ds_read_b128 v[202:205], v161 offset:38912
	ds_read_b128 v[212:215], v161 offset:39936
	global_load_lds_dwordx4 v[222:223], off
	v_lshl_add_u64 v[222:223], s[22:23], 0, v[146:147]
	s_mov_b32 m0, s28
	s_nop 0
	global_load_lds_dwordx4 v[222:223], off
	s_waitcnt vmcnt(8)
	s_waitcnt lgkmcnt(0)
	s_barrier
	s_waitcnt lgkmcnt(0)
	v_mfma_f32_16x16x32_bf16 v[140:143], v[64:67], v[178:181], v[140:143]
	v_mfma_f32_16x16x32_bf16 v[136:139], v[72:75], v[178:181], v[136:139]
	v_mfma_f32_16x16x32_bf16 v[132:135], v[64:67], v[186:189], v[132:135]
	v_mfma_f32_16x16x32_bf16 v[128:131], v[72:75], v[186:189], v[128:131]
	v_mfma_f32_16x16x32_bf16 v[108:111], v[64:67], v[194:197], v[108:111]
	v_mfma_f32_16x16x32_bf16 v[104:107], v[72:75], v[194:197], v[104:107]
	v_mfma_f32_16x16x32_bf16 v[100:103], v[64:67], v[202:205], v[100:103]
	v_mfma_f32_16x16x32_bf16 v[96:99], v[72:75], v[202:205], v[96:99]
	v_mfma_f32_16x16x32_bf16 v[140:143], v[68:71], v[182:185], v[140:143]
	v_mfma_f32_16x16x32_bf16 v[136:139], v[76:79], v[182:185], v[136:139]
	v_mfma_f32_16x16x32_bf16 v[132:135], v[68:71], v[190:193], v[132:135]
	v_mfma_f32_16x16x32_bf16 v[128:131], v[76:79], v[190:193], v[128:131]
	v_mfma_f32_16x16x32_bf16 v[108:111], v[68:71], v[198:201], v[108:111]
	v_mfma_f32_16x16x32_bf16 v[104:107], v[76:79], v[198:201], v[104:107]
	v_mfma_f32_16x16x32_bf16 v[100:103], v[68:71], v[212:215], v[100:103]
	v_mfma_f32_16x16x32_bf16 v[96:99], v[76:79], v[212:215], v[96:99]
	v_mfma_f32_16x16x32_bf16 v[124:127], v[154:157], v[178:181], v[124:127]
	v_mfma_f32_16x16x32_bf16 v[120:123], v[170:173], v[178:181], v[120:123]
	v_mfma_f32_16x16x32_bf16 v[116:119], v[154:157], v[186:189], v[116:119]
	v_mfma_f32_16x16x32_bf16 v[112:115], v[170:173], v[186:189], v[112:115]
	v_mfma_f32_16x16x32_bf16 v[92:95], v[154:157], v[194:197], v[92:95]
	v_mfma_f32_16x16x32_bf16 v[88:91], v[170:173], v[194:197], v[88:91]
	v_mfma_f32_16x16x32_bf16 v[84:87], v[154:157], v[202:205], v[84:87]
	v_mfma_f32_16x16x32_bf16 v[80:83], v[170:173], v[202:205], v[80:83]
	v_mfma_f32_16x16x32_bf16 v[124:127], v[162:165], v[182:185], v[124:127]
	v_mfma_f32_16x16x32_bf16 v[120:123], v[174:177], v[182:185], v[120:123]
	v_mfma_f32_16x16x32_bf16 v[116:119], v[162:165], v[190:193], v[116:119]
	v_mfma_f32_16x16x32_bf16 v[112:115], v[174:177], v[190:193], v[112:115]
	v_mfma_f32_16x16x32_bf16 v[92:95], v[162:165], v[198:201], v[92:95]
	v_mfma_f32_16x16x32_bf16 v[88:91], v[174:177], v[198:201], v[88:91]
	v_mfma_f32_16x16x32_bf16 v[84:87], v[162:165], v[212:215], v[84:87]
	v_mfma_f32_16x16x32_bf16 v[80:83], v[174:177], v[212:215], v[80:83]
	s_barrier
	s_add_i32 s22, s47, s24
	v_lshl_add_u64 v[166:167], v[166:167], 0, s[74:75]
	s_mov_b32 m0, s22
	ds_read_b128 v[178:181], v161 offset:49152
	ds_read_b128 v[182:185], v161 offset:50176
	ds_read_b128 v[186:189], v161 offset:51200
	ds_read_b128 v[190:193], v161 offset:52224
	ds_read_b128 v[194:197], v161 offset:53248
	ds_read_b128 v[198:201], v161 offset:54272
	ds_read_b128 v[202:205], v161 offset:55296
	ds_read_b128 v[212:215], v161 offset:56320
	global_load_lds_dwordx4 v[166:167], off
	s_add_i32 m0, s22, 0x2000
	s_add_u32 s20, s20, 0x40080
	v_lshl_add_u64 v[166:167], v[216:217], 0, s[74:75]
	s_addc_u32 s21, s21, 0
	s_add_i32 s22, s48, s24
	global_load_lds_dwordx4 v[166:167], off
	v_lshl_add_u64 v[166:167], s[20:21], 0, v[168:169]
	s_mov_b32 m0, s22
	s_nop 0
	global_load_lds_dwordx4 v[166:167], off
	v_lshl_add_u64 v[166:167], s[20:21], 0, v[144:145]
	s_add_i32 m0, s22, 0x2000
	s_nop 0
	global_load_lds_dwordx4 v[166:167], off
	v_lshl_add_u64 v[166:167], v[218:219], 0, s[74:75]
	s_mov_b32 m0, s31
	s_nop 0
	global_load_lds_dwordx4 v[166:167], off
	v_lshl_add_u64 v[166:167], v[220:221], 0, s[74:75]
	s_mov_b32 m0, s38
	s_nop 0
	global_load_lds_dwordx4 v[166:167], off
	s_waitcnt vmcnt(8)
	s_waitcnt lgkmcnt(0)
	s_barrier
	s_waitcnt lgkmcnt(0)
	v_mfma_f32_16x16x32_bf16 v[60:63], v[64:67], v[178:181], v[60:63]
	v_mfma_f32_16x16x32_bf16 v[56:59], v[72:75], v[178:181], v[56:59]
	v_mfma_f32_16x16x32_bf16 v[52:55], v[64:67], v[186:189], v[52:55]
	v_mfma_f32_16x16x32_bf16 v[48:51], v[72:75], v[186:189], v[48:51]
	v_mfma_f32_16x16x32_bf16 v[28:31], v[64:67], v[194:197], v[28:31]
	v_mfma_f32_16x16x32_bf16 v[24:27], v[72:75], v[194:197], v[24:27]
	v_mfma_f32_16x16x32_bf16 v[20:23], v[64:67], v[202:205], v[20:23]
	v_mfma_f32_16x16x32_bf16 v[16:19], v[72:75], v[202:205], v[16:19]
	v_mfma_f32_16x16x32_bf16 v[60:63], v[68:71], v[182:185], v[60:63]
	v_mfma_f32_16x16x32_bf16 v[56:59], v[76:79], v[182:185], v[56:59]
	v_mfma_f32_16x16x32_bf16 v[52:55], v[68:71], v[190:193], v[52:55]
	v_mfma_f32_16x16x32_bf16 v[48:51], v[76:79], v[190:193], v[48:51]
	v_mfma_f32_16x16x32_bf16 v[28:31], v[68:71], v[198:201], v[28:31]
	v_mfma_f32_16x16x32_bf16 v[24:27], v[76:79], v[198:201], v[24:27]
	v_mfma_f32_16x16x32_bf16 v[20:23], v[68:71], v[212:215], v[20:23]
	v_mfma_f32_16x16x32_bf16 v[16:19], v[76:79], v[212:215], v[16:19]
	v_mfma_f32_16x16x32_bf16 v[44:47], v[154:157], v[178:181], v[44:47]
	v_mfma_f32_16x16x32_bf16 v[40:43], v[170:173], v[178:181], v[40:43]
	v_mfma_f32_16x16x32_bf16 v[36:39], v[154:157], v[186:189], v[36:39]
	v_mfma_f32_16x16x32_bf16 v[32:35], v[170:173], v[186:189], v[32:35]
	v_mfma_f32_16x16x32_bf16 v[12:15], v[154:157], v[194:197], v[12:15]
	v_mfma_f32_16x16x32_bf16 v[8:11], v[170:173], v[194:197], v[8:11]
	v_mfma_f32_16x16x32_bf16 v[4:7], v[154:157], v[202:205], v[4:7]
	v_mfma_f32_16x16x32_bf16 v[0:3], v[170:173], v[202:205], v[0:3]
	v_mfma_f32_16x16x32_bf16 v[44:47], v[162:165], v[182:185], v[44:47]
	v_mfma_f32_16x16x32_bf16 v[40:43], v[174:177], v[182:185], v[40:43]
	v_mfma_f32_16x16x32_bf16 v[36:39], v[162:165], v[190:193], v[36:39]
	v_mfma_f32_16x16x32_bf16 v[32:35], v[174:177], v[190:193], v[32:35]
	v_mfma_f32_16x16x32_bf16 v[12:15], v[162:165], v[198:201], v[12:15]
	v_mfma_f32_16x16x32_bf16 v[8:11], v[174:177], v[198:201], v[8:11]
	v_mfma_f32_16x16x32_bf16 v[4:7], v[162:165], v[212:215], v[4:7]
	v_mfma_f32_16x16x32_bf16 v[0:3], v[174:177], v[212:215], v[0:3]
	s_barrier
	s_add_i32 s46, s46, 2
	s_add_u32 s44, s44, 0x100
	s_addc_u32 s45, s45, 0
	s_add_u32 s18, s18, 0x100
	s_addc_u32 s19, s19, 0
	s_cmp_gt_u32 s46, 13
	s_cbranch_scc0 .LBB0_655
	s_and_b64 vcc, exec, s[8:9]
	s_cbranch_vccz .LBB0_658
	s_barrier

.LBB0_947:
	s_add_u32 s46, s18, 0x100
	v_mov_b32_e32 v0, 0
	s_addc_u32 s47, s19, 0
	s_mov_b32 s48, -2
	s_add_u32 s18, s16, 0x100
	s_addc_u32 s19, s17, 0
	s_add_i32 s49, 0, 0x10000
	s_cmp_eq_u32 s48, 40
	s_cselect_b32 s23, s3, s19
	s_cselect_b32 s22, s2, s18
	s_cselect_b32 s21, s15, s47
	s_cselect_b32 s20, s14, s46
	s_add_i32 s50, 0, 0x14000
	v_add_u32_e32 v140, s49, v163
	v_add_u32_e32 v166, s50, v163
	ds_read_b128 v[128:131], v140
	ds_read_b128 v[132:135], v140 offset:1024
	ds_read_b128 v[136:139], v140 offset:2048
	ds_read_b128 v[140:143], v140 offset:3072
	ds_read_b128 v[154:157], v166
	ds_read_b128 v[158:161], v166 offset:1024
	ds_read_b128 v[170:173], v166 offset:2048
	ds_read_b128 v[174:177], v166 offset:3072
	v_lshl_add_u64 v[166:167], s[16:17], 0, v[152:153]
	s_add_i32 m0, s25, 0xc000
	ds_read_b128 v[178:181], v165
	ds_read_b128 v[182:185], v165 offset:1024
	ds_read_b128 v[186:189], v165 offset:2048
	ds_read_b128 v[190:193], v165 offset:3072
	ds_read_b128 v[194:197], v165 offset:4096
	ds_read_b128 v[198:201], v165 offset:5120
	ds_read_b128 v[212:215], v165 offset:6144
	ds_read_b128 v[216:219], v165 offset:7168
	global_load_lds_dwordx4 v[166:167], off
	v_lshl_add_u64 v[166:167], s[16:17], 0, v[150:151]
	s_add_i32 m0, s25, 0xe000
	s_nop 0
	global_load_lds_dwordx4 v[166:167], off
	s_waitcnt vmcnt(8)
	s_waitcnt lgkmcnt(0)
	s_barrier
	s_waitcnt lgkmcnt(0)
	v_mfma_f32_16x16x32_bf16 v[124:127], v[128:131], v[178:181], 0
	v_mfma_f32_16x16x32_bf16 v[120:123], v[136:139], v[178:181], 0
	v_mfma_f32_16x16x32_bf16 v[116:119], v[128:131], v[186:189], 0
	v_mfma_f32_16x16x32_bf16 v[112:115], v[136:139], v[186:189], 0
	v_mfma_f32_16x16x32_bf16 v[92:95], v[128:131], v[194:197], 0
	v_mfma_f32_16x16x32_bf16 v[88:91], v[136:139], v[194:197], 0
	v_mfma_f32_16x16x32_bf16 v[76:79], v[128:131], v[212:215], 0
	v_mfma_f32_16x16x32_bf16 v[72:75], v[136:139], v[212:215], 0
	v_mfma_f32_16x16x32_bf16 v[124:127], v[132:135], v[182:185], v[124:127]
	v_mfma_f32_16x16x32_bf16 v[120:123], v[140:143], v[182:185], v[120:123]
	v_mfma_f32_16x16x32_bf16 v[116:119], v[132:135], v[190:193], v[116:119]
	v_mfma_f32_16x16x32_bf16 v[112:115], v[140:143], v[190:193], v[112:115]
	v_mfma_f32_16x16x32_bf16 v[92:95], v[132:135], v[198:201], v[92:95]
	v_mfma_f32_16x16x32_bf16 v[88:91], v[140:143], v[198:201], v[88:91]
	v_mfma_f32_16x16x32_bf16 v[76:79], v[132:135], v[216:219], v[76:79]
	v_mfma_f32_16x16x32_bf16 v[72:75], v[140:143], v[216:219], v[72:75]
	v_mfma_f32_16x16x32_bf16 v[108:111], v[154:157], v[178:181], 0
	v_mfma_f32_16x16x32_bf16 v[104:107], v[170:173], v[178:181], 0
	v_mfma_f32_16x16x32_bf16 v[100:103], v[154:157], v[186:189], 0
	v_mfma_f32_16x16x32_bf16 v[96:99], v[170:173], v[186:189], 0
	v_mfma_f32_16x16x32_bf16 v[84:87], v[154:157], v[194:197], 0
	v_mfma_f32_16x16x32_bf16 v[80:83], v[170:173], v[194:197], 0
	v_mfma_f32_16x16x32_bf16 v[68:71], v[154:157], v[212:215], 0
	v_mfma_f32_16x16x32_bf16 v[64:67], v[170:173], v[212:215], 0
	v_mfma_f32_16x16x32_bf16 v[108:111], v[158:161], v[182:185], v[108:111]
	v_mfma_f32_16x16x32_bf16 v[104:107], v[174:177], v[182:185], v[104:107]
	v_mfma_f32_16x16x32_bf16 v[100:103], v[158:161], v[190:193], v[100:103]
	v_mfma_f32_16x16x32_bf16 v[96:99], v[174:177], v[190:193], v[96:99]
	v_mfma_f32_16x16x32_bf16 v[84:87], v[158:161], v[198:201], v[84:87]
	v_mfma_f32_16x16x32_bf16 v[80:83], v[174:177], v[198:201], v[80:83]
	v_mfma_f32_16x16x32_bf16 v[68:71], v[158:161], v[216:219], v[68:71]
	v_mfma_f32_16x16x32_bf16 v[64:67], v[174:177], v[216:219], v[64:67]
	s_barrier
	s_add_i32 s16, s49, s24
	v_lshl_add_u64 v[166:167], s[20:21], 0, v[168:169]
	s_mov_b32 m0, s16
	ds_read_b128 v[178:181], v165 offset:16384
	ds_read_b128 v[182:185], v165 offset:17408
	ds_read_b128 v[186:189], v165 offset:18432
	ds_read_b128 v[190:193], v165 offset:19456
	ds_read_b128 v[194:197], v165 offset:20480
	ds_read_b128 v[198:201], v165 offset:21504
	ds_read_b128 v[212:215], v165 offset:22528
	ds_read_b128 v[216:219], v165 offset:23552
	global_load_lds_dwordx4 v[166:167], off
	s_add_i32 m0, s16, 0x2000
	s_add_u32 s16, s20, 0xb0000
	v_lshl_add_u64 v[202:203], s[20:21], 0, v[144:145]
	s_addc_u32 s17, s21, 0
	s_add_i32 s49, s50, s24
	global_load_lds_dwordx4 v[202:203], off
	v_lshl_add_u64 v[220:221], s[16:17], 0, v[168:169]
	s_mov_b32 m0, s49
	v_lshl_add_u64 v[222:223], s[22:23], 0, v[146:147]
	global_load_lds_dwordx4 v[220:221], off
	v_lshl_add_u64 v[220:221], s[16:17], 0, v[144:145]
	s_add_i32 m0, s49, 0x2000
	s_nop 0
	global_load_lds_dwordx4 v[220:221], off
	v_lshl_add_u64 v[220:221], s[22:23], 0, v[148:149]
	s_mov_b32 m0, s25
	s_nop 0
	global_load_lds_dwordx4 v[220:221], off
	s_mov_b32 m0, s36
	s_nop 0
	global_load_lds_dwordx4 v[222:223], off
	s_waitcnt vmcnt(8)
	s_waitcnt lgkmcnt(0)
	s_barrier
	s_waitcnt lgkmcnt(0)
	v_mfma_f32_16x16x32_bf16 v[60:63], v[128:131], v[178:181], 0
	v_mfma_f32_16x16x32_bf16 v[56:59], v[136:139], v[178:181], 0
	v_mfma_f32_16x16x32_bf16 v[44:47], v[128:131], v[186:189], 0
	v_mfma_f32_16x16x32_bf16 v[40:43], v[136:139], v[186:189], 0
	v_mfma_f32_16x16x32_bf16 v[28:31], v[128:131], v[194:197], 0
	v_mfma_f32_16x16x32_bf16 v[24:27], v[136:139], v[194:197], 0
	v_mfma_f32_16x16x32_bf16 v[12:15], v[128:131], v[212:215], 0
	v_mfma_f32_16x16x32_bf16 v[8:11], v[136:139], v[212:215], 0
	v_mfma_f32_16x16x32_bf16 v[60:63], v[132:135], v[182:185], v[60:63]
	v_mfma_f32_16x16x32_bf16 v[56:59], v[140:143], v[182:185], v[56:59]
	v_mfma_f32_16x16x32_bf16 v[44:47], v[132:135], v[190:193], v[44:47]
	v_mfma_f32_16x16x32_bf16 v[40:43], v[140:143], v[190:193], v[40:43]
	v_mfma_f32_16x16x32_bf16 v[28:31], v[132:135], v[198:201], v[28:31]
	v_mfma_f32_16x16x32_bf16 v[24:27], v[140:143], v[198:201], v[24:27]
	v_mfma_f32_16x16x32_bf16 v[12:15], v[132:135], v[216:219], v[12:15]
	v_mfma_f32_16x16x32_bf16 v[8:11], v[140:143], v[216:219], v[8:11]
	v_mfma_f32_16x16x32_bf16 v[52:55], v[154:157], v[178:181], 0
	v_mfma_f32_16x16x32_bf16 v[48:51], v[170:173], v[178:181], 0
	v_mfma_f32_16x16x32_bf16 v[36:39], v[154:157], v[186:189], 0
	v_mfma_f32_16x16x32_bf16 v[32:35], v[170:173], v[186:189], 0
	v_mfma_f32_16x16x32_bf16 v[20:23], v[154:157], v[194:197], 0
	v_mfma_f32_16x16x32_bf16 v[16:19], v[170:173], v[194:197], 0
	v_mfma_f32_16x16x32_bf16 v[4:7], v[154:157], v[212:215], 0
	v_mfma_f32_16x16x32_bf16 v[0:3], v[170:173], v[212:215], 0
	v_mfma_f32_16x16x32_bf16 v[52:55], v[158:161], v[182:185], v[52:55]
	v_mfma_f32_16x16x32_bf16 v[48:51], v[174:177], v[182:185], v[48:51]
	v_mfma_f32_16x16x32_bf16 v[36:39], v[158:161], v[190:193], v[36:39]
	v_mfma_f32_16x16x32_bf16 v[32:35], v[174:177], v[190:193], v[32:35]
	v_mfma_f32_16x16x32_bf16 v[20:23], v[158:161], v[198:201], v[20:23]
	v_mfma_f32_16x16x32_bf16 v[16:19], v[174:177], v[198:201], v[16:19]
	v_mfma_f32_16x16x32_bf16 v[4:7], v[158:161], v[216:219], v[4:7]
	v_mfma_f32_16x16x32_bf16 v[0:3], v[174:177], v[216:219], v[0:3]
	s_barrier
	s_branch .Lpeel_p9a

.Lpeel_p9a:
	s_add_i32 s49, 0, 0x18000
	s_add_i32 s50, 0, 0x1c000
	v_add_u32_e32 v140, s49, v163
	v_add_u32_e32 v174, s50, v163
	ds_read_b128 v[128:131], v140
	ds_read_b128 v[132:135], v140 offset:1024
	ds_read_b128 v[136:139], v140 offset:2048
	ds_read_b128 v[140:143], v140 offset:3072
	ds_read_b128 v[154:157], v174
	ds_read_b128 v[158:161], v174 offset:1024
	ds_read_b128 v[170:173], v174 offset:2048
	ds_read_b128 v[174:177], v174 offset:3072
	s_add_u32 s16, s22, 0xb0000
	s_addc_u32 s17, s23, 0
	s_mov_b32 m0, s37
	v_lshl_add_u64 v[224:225], s[16:17], 0, v[148:149]
	ds_read_b128 v[178:181], v165 offset:32768
	ds_read_b128 v[182:185], v165 offset:33792
	ds_read_b128 v[186:189], v165 offset:34816
	ds_read_b128 v[190:193], v165 offset:35840
	ds_read_b128 v[194:197], v165 offset:36864
	ds_read_b128 v[198:201], v165 offset:37888
	ds_read_b128 v[212:215], v165 offset:38912
	ds_read_b128 v[216:219], v165 offset:39936
	global_load_lds_dwordx4 v[224:225], off
	v_lshl_add_u64 v[224:225], s[16:17], 0, v[146:147]
	s_mov_b32 m0, s38
	s_nop 0
	global_load_lds_dwordx4 v[224:225], off
	s_waitcnt vmcnt(8)
	s_waitcnt lgkmcnt(0)
	s_barrier
	s_waitcnt lgkmcnt(0)
	v_mfma_f32_16x16x32_bf16 v[124:127], v[128:131], v[178:181], v[124:127]
	v_mfma_f32_16x16x32_bf16 v[120:123], v[136:139], v[178:181], v[120:123]
	v_mfma_f32_16x16x32_bf16 v[116:119], v[128:131], v[186:189], v[116:119]
	v_mfma_f32_16x16x32_bf16 v[112:115], v[136:139], v[186:189], v[112:115]
	v_mfma_f32_16x16x32_bf16 v[92:95], v[128:131], v[194:197], v[92:95]
	v_mfma_f32_16x16x32_bf16 v[88:91], v[136:139], v[194:197], v[88:91]
	v_mfma_f32_16x16x32_bf16 v[76:79], v[128:131], v[212:215], v[76:79]
	v_mfma_f32_16x16x32_bf16 v[72:75], v[136:139], v[212:215], v[72:75]
	v_mfma_f32_16x16x32_bf16 v[124:127], v[132:135], v[182:185], v[124:127]
	v_mfma_f32_16x16x32_bf16 v[120:123], v[140:143], v[182:185], v[120:123]
	v_mfma_f32_16x16x32_bf16 v[116:119], v[132:135], v[190:193], v[116:119]
	v_mfma_f32_16x16x32_bf16 v[112:115], v[140:143], v[190:193], v[112:115]
	v_mfma_f32_16x16x32_bf16 v[92:95], v[132:135], v[198:201], v[92:95]
	v_mfma_f32_16x16x32_bf16 v[88:91], v[140:143], v[198:201], v[88:91]
	v_mfma_f32_16x16x32_bf16 v[76:79], v[132:135], v[216:219], v[76:79]
	v_mfma_f32_16x16x32_bf16 v[72:75], v[140:143], v[216:219], v[72:75]
	v_mfma_f32_16x16x32_bf16 v[108:111], v[154:157], v[178:181], v[108:111]
	v_mfma_f32_16x16x32_bf16 v[104:107], v[170:173], v[178:181], v[104:107]
	v_mfma_f32_16x16x32_bf16 v[100:103], v[154:157], v[186:189], v[100:103]
	v_mfma_f32_16x16x32_bf16 v[96:99], v[170:173], v[186:189], v[96:99]
	v_mfma_f32_16x16x32_bf16 v[84:87], v[154:157], v[194:197], v[84:87]
	v_mfma_f32_16x16x32_bf16 v[80:83], v[170:173], v[194:197], v[80:83]
	v_mfma_f32_16x16x32_bf16 v[68:71], v[154:157], v[212:215], v[68:71]
	v_mfma_f32_16x16x32_bf16 v[64:67], v[170:173], v[212:215], v[64:67]
	v_mfma_f32_16x16x32_bf16 v[108:111], v[158:161], v[182:185], v[108:111]
	v_mfma_f32_16x16x32_bf16 v[104:107], v[174:177], v[182:185], v[104:107]
	v_mfma_f32_16x16x32_bf16 v[100:103], v[158:161], v[190:193], v[100:103]
	v_mfma_f32_16x16x32_bf16 v[96:99], v[174:177], v[190:193], v[96:99]
	v_mfma_f32_16x16x32_bf16 v[84:87], v[158:161], v[198:201], v[84:87]
	v_mfma_f32_16x16x32_bf16 v[80:83], v[174:177], v[198:201], v[80:83]
	v_mfma_f32_16x16x32_bf16 v[68:71], v[158:161], v[216:219], v[68:71]
	v_mfma_f32_16x16x32_bf16 v[64:67], v[174:177], v[216:219], v[64:67]
	s_barrier
	s_add_i32 s16, s49, s24
	v_lshl_add_u64 v[166:167], v[166:167], 0, s[74:75]
	s_mov_b32 m0, s16
	ds_read_b128 v[178:181], v165 offset:49152
	ds_read_b128 v[182:185], v165 offset:50176
	ds_read_b128 v[186:189], v165 offset:51200
	ds_read_b128 v[190:193], v165 offset:52224
	ds_read_b128 v[194:197], v165 offset:53248
	ds_read_b128 v[198:201], v165 offset:54272
	ds_read_b128 v[212:215], v165 offset:55296
	ds_read_b128 v[216:219], v165 offset:56320
	global_load_lds_dwordx4 v[166:167], off
	s_add_i32 m0, s16, 0x2000
	s_add_u32 s16, s20, 0xb0080
	v_lshl_add_u64 v[166:167], v[202:203], 0, s[74:75]
	s_addc_u32 s17, s21, 0
	s_add_i32 s20, s50, s24
	global_load_lds_dwordx4 v[166:167], off
	v_lshl_add_u64 v[166:167], s[16:17], 0, v[168:169]
	s_mov_b32 m0, s20
	s_nop 0
	global_load_lds_dwordx4 v[166:167], off
	v_lshl_add_u64 v[166:167], s[16:17], 0, v[144:145]
	s_add_i32 m0, s20, 0x2000
	s_nop 0
	global_load_lds_dwordx4 v[166:167], off
	v_lshl_add_u64 v[166:167], v[220:221], 0, s[74:75]
	s_mov_b32 m0, s39
	s_nop 0
	global_load_lds_dwordx4 v[166:167], off
	v_lshl_add_u64 v[166:167], v[222:223], 0, s[74:75]
	s_mov_b32 m0, s40
	s_nop 0
	global_load_lds_dwordx4 v[166:167], off
	s_waitcnt vmcnt(8)
	s_waitcnt lgkmcnt(0)
	s_barrier
	s_waitcnt lgkmcnt(0)
	v_mfma_f32_16x16x32_bf16 v[60:63], v[128:131], v[178:181], v[60:63]
	v_mfma_f32_16x16x32_bf16 v[56:59], v[136:139], v[178:181], v[56:59]
	v_mfma_f32_16x16x32_bf16 v[44:47], v[128:131], v[186:189], v[44:47]
	v_mfma_f32_16x16x32_bf16 v[40:43], v[136:139], v[186:189], v[40:43]
	v_mfma_f32_16x16x32_bf16 v[28:31], v[128:131], v[194:197], v[28:31]
	v_mfma_f32_16x16x32_bf16 v[24:27], v[136:139], v[194:197], v[24:27]
	v_mfma_f32_16x16x32_bf16 v[12:15], v[128:131], v[212:215], v[12:15]
	v_mfma_f32_16x16x32_bf16 v[8:11], v[136:139], v[212:215], v[8:11]
	v_mfma_f32_16x16x32_bf16 v[60:63], v[132:135], v[182:185], v[60:63]
	v_mfma_f32_16x16x32_bf16 v[56:59], v[140:143], v[182:185], v[56:59]
	v_mfma_f32_16x16x32_bf16 v[44:47], v[132:135], v[190:193], v[44:47]
	v_mfma_f32_16x16x32_bf16 v[40:43], v[140:143], v[190:193], v[40:43]
	v_mfma_f32_16x16x32_bf16 v[28:31], v[132:135], v[198:201], v[28:31]
	v_mfma_f32_16x16x32_bf16 v[24:27], v[140:143], v[198:201], v[24:27]
	v_mfma_f32_16x16x32_bf16 v[12:15], v[132:135], v[216:219], v[12:15]
	v_mfma_f32_16x16x32_bf16 v[8:11], v[140:143], v[216:219], v[8:11]
	v_mfma_f32_16x16x32_bf16 v[52:55], v[154:157], v[178:181], v[52:55]
	v_mfma_f32_16x16x32_bf16 v[48:51], v[170:173], v[178:181], v[48:51]
	v_mfma_f32_16x16x32_bf16 v[36:39], v[154:157], v[186:189], v[36:39]
	v_mfma_f32_16x16x32_bf16 v[32:35], v[170:173], v[186:189], v[32:35]
	v_mfma_f32_16x16x32_bf16 v[20:23], v[154:157], v[194:197], v[20:23]
	v_mfma_f32_16x16x32_bf16 v[16:19], v[170:173], v[194:197], v[16:19]
	v_mfma_f32_16x16x32_bf16 v[4:7], v[154:157], v[212:215], v[4:7]
	v_mfma_f32_16x16x32_bf16 v[0:3], v[170:173], v[212:215], v[0:3]
	v_mfma_f32_16x16x32_bf16 v[52:55], v[158:161], v[182:185], v[52:55]
	v_mfma_f32_16x16x32_bf16 v[48:51], v[174:177], v[182:185], v[48:51]
	v_mfma_f32_16x16x32_bf16 v[36:39], v[158:161], v[190:193], v[36:39]
	v_mfma_f32_16x16x32_bf16 v[32:35], v[174:177], v[190:193], v[32:35]
	v_mfma_f32_16x16x32_bf16 v[20:23], v[158:161], v[198:201], v[20:23]
	v_mfma_f32_16x16x32_bf16 v[16:19], v[174:177], v[198:201], v[16:19]
	v_mfma_f32_16x16x32_bf16 v[4:7], v[158:161], v[216:219], v[4:7]
	v_mfma_f32_16x16x32_bf16 v[0:3], v[174:177], v[216:219], v[0:3]
	s_barrier
	s_add_i32 s48, s48, 2
	s_add_u32 s46, s46, 0x100
	s_addc_u32 s47, s47, 0
	s_cmp_gt_u32 s48, 41
	s_mov_b64 s[16:17], s[18:19]
	s_cbranch_scc0 .LBB0_948
	s_and_b64 vcc, exec, s[10:11]
	s_cbranch_vccz .LBB0_951
	s_barrier

.LBB0_1031:
	s_add_u32 s40, s14, 0x100
	v_mov_b32_e32 v0, 0
	s_addc_u32 s41, s15, 0
	s_mov_b32 s42, -2
	s_add_u32 s14, s12, 0x100
	s_addc_u32 s15, s13, 0
	s_add_i32 s43, 0, 0x10000
	s_cmp_eq_u32 s42, 40
	s_cselect_b32 s19, s3, s15
	s_cselect_b32 s18, s2, s14
	s_cselect_b32 s17, s11, s41
	s_cselect_b32 s16, s10, s40
	s_add_i32 s44, 0, 0x14000
	v_add_u32_e32 v140, s43, v163
	v_add_u32_e32 v166, s44, v163
	ds_read_b128 v[128:131], v140
	ds_read_b128 v[132:135], v140 offset:1024
	ds_read_b128 v[136:139], v140 offset:2048
	ds_read_b128 v[140:143], v140 offset:3072
	ds_read_b128 v[154:157], v166
	ds_read_b128 v[158:161], v166 offset:1024
	ds_read_b128 v[170:173], v166 offset:2048
	ds_read_b128 v[174:177], v166 offset:3072
	v_lshl_add_u64 v[166:167], s[12:13], 0, v[152:153]
	s_add_i32 m0, s21, 0xc000
	ds_read_b128 v[178:181], v165
	ds_read_b128 v[182:185], v165 offset:1024
	ds_read_b128 v[186:189], v165 offset:2048
	ds_read_b128 v[190:193], v165 offset:3072
	ds_read_b128 v[194:197], v165 offset:4096
	ds_read_b128 v[198:201], v165 offset:5120
	ds_read_b128 v[202:205], v165 offset:6144
	ds_read_b128 v[212:215], v165 offset:7168
	global_load_lds_dwordx4 v[166:167], off
	v_lshl_add_u64 v[166:167], s[12:13], 0, v[150:151]
	s_add_i32 m0, s21, 0xe000
	s_nop 0
	global_load_lds_dwordx4 v[166:167], off
	s_waitcnt vmcnt(8)
	s_waitcnt lgkmcnt(0)
	s_barrier
	s_waitcnt lgkmcnt(0)
	v_mfma_f32_16x16x32_bf16 v[124:127], v[128:131], v[178:181], 0
	v_mfma_f32_16x16x32_bf16 v[120:123], v[136:139], v[178:181], 0
	v_mfma_f32_16x16x32_bf16 v[112:115], v[128:131], v[186:189], 0
	v_mfma_f32_16x16x32_bf16 v[104:107], v[136:139], v[186:189], 0
	v_mfma_f32_16x16x32_bf16 v[92:95], v[128:131], v[194:197], 0
	v_mfma_f32_16x16x32_bf16 v[88:91], v[136:139], v[194:197], 0
	v_mfma_f32_16x16x32_bf16 v[76:79], v[128:131], v[202:205], 0
	v_mfma_f32_16x16x32_bf16 v[72:75], v[136:139], v[202:205], 0
	v_mfma_f32_16x16x32_bf16 v[124:127], v[132:135], v[182:185], v[124:127]
	v_mfma_f32_16x16x32_bf16 v[120:123], v[140:143], v[182:185], v[120:123]
	v_mfma_f32_16x16x32_bf16 v[112:115], v[132:135], v[190:193], v[112:115]
	v_mfma_f32_16x16x32_bf16 v[104:107], v[140:143], v[190:193], v[104:107]
	v_mfma_f32_16x16x32_bf16 v[92:95], v[132:135], v[198:201], v[92:95]
	v_mfma_f32_16x16x32_bf16 v[88:91], v[140:143], v[198:201], v[88:91]
	v_mfma_f32_16x16x32_bf16 v[76:79], v[132:135], v[212:215], v[76:79]
	v_mfma_f32_16x16x32_bf16 v[72:75], v[140:143], v[212:215], v[72:75]
	v_mfma_f32_16x16x32_bf16 v[116:119], v[154:157], v[178:181], 0
	v_mfma_f32_16x16x32_bf16 v[108:111], v[170:173], v[178:181], 0
	v_mfma_f32_16x16x32_bf16 v[100:103], v[154:157], v[186:189], 0
	v_mfma_f32_16x16x32_bf16 v[96:99], v[170:173], v[186:189], 0
	v_mfma_f32_16x16x32_bf16 v[84:87], v[154:157], v[194:197], 0
	v_mfma_f32_16x16x32_bf16 v[80:83], v[170:173], v[194:197], 0
	v_mfma_f32_16x16x32_bf16 v[68:71], v[154:157], v[202:205], 0
	v_mfma_f32_16x16x32_bf16 v[64:67], v[170:173], v[202:205], 0
	v_mfma_f32_16x16x32_bf16 v[116:119], v[158:161], v[182:185], v[116:119]
	v_mfma_f32_16x16x32_bf16 v[108:111], v[174:177], v[182:185], v[108:111]
	v_mfma_f32_16x16x32_bf16 v[100:103], v[158:161], v[190:193], v[100:103]
	v_mfma_f32_16x16x32_bf16 v[96:99], v[174:177], v[190:193], v[96:99]
	v_mfma_f32_16x16x32_bf16 v[84:87], v[158:161], v[198:201], v[84:87]
	v_mfma_f32_16x16x32_bf16 v[80:83], v[174:177], v[198:201], v[80:83]
	v_mfma_f32_16x16x32_bf16 v[68:71], v[158:161], v[212:215], v[68:71]
	v_mfma_f32_16x16x32_bf16 v[64:67], v[174:177], v[212:215], v[64:67]
	s_barrier
	s_add_i32 s12, s43, s20
	v_lshl_add_u64 v[166:167], s[16:17], 0, v[168:169]
	s_mov_b32 m0, s12
	ds_read_b128 v[178:181], v165 offset:16384
	ds_read_b128 v[182:185], v165 offset:17408
	ds_read_b128 v[186:189], v165 offset:18432
	ds_read_b128 v[190:193], v165 offset:19456
	ds_read_b128 v[194:197], v165 offset:20480
	ds_read_b128 v[198:201], v165 offset:21504
	ds_read_b128 v[202:205], v165 offset:22528
	ds_read_b128 v[212:215], v165 offset:23552
	global_load_lds_dwordx4 v[166:167], off
	s_add_i32 m0, s12, 0x2000
	s_add_u32 s12, s16, 0xb0000
	v_lshl_add_u64 v[216:217], s[16:17], 0, v[144:145]
	s_addc_u32 s13, s17, 0
	s_add_i32 s43, s44, s20
	global_load_lds_dwordx4 v[216:217], off
	v_lshl_add_u64 v[218:219], s[12:13], 0, v[168:169]
	s_mov_b32 m0, s43
	v_lshl_add_u64 v[220:221], s[18:19], 0, v[146:147]
	global_load_lds_dwordx4 v[218:219], off
	v_lshl_add_u64 v[218:219], s[12:13], 0, v[144:145]
	s_add_i32 m0, s43, 0x2000
	s_nop 0
	global_load_lds_dwordx4 v[218:219], off
	v_lshl_add_u64 v[218:219], s[18:19], 0, v[148:149]
	s_mov_b32 m0, s21
	s_nop 0
	global_load_lds_dwordx4 v[218:219], off
	s_mov_b32 m0, s22
	s_nop 0
	global_load_lds_dwordx4 v[220:221], off
	s_waitcnt vmcnt(8)
	s_waitcnt lgkmcnt(0)
	s_barrier
	s_waitcnt lgkmcnt(0)
	v_mfma_f32_16x16x32_bf16 v[60:63], v[128:131], v[178:181], 0
	v_mfma_f32_16x16x32_bf16 v[56:59], v[136:139], v[178:181], 0
	v_mfma_f32_16x16x32_bf16 v[44:47], v[128:131], v[186:189], 0
	v_mfma_f32_16x16x32_bf16 v[40:43], v[136:139], v[186:189], 0
	v_mfma_f32_16x16x32_bf16 v[28:31], v[128:131], v[194:197], 0
	v_mfma_f32_16x16x32_bf16 v[24:27], v[136:139], v[194:197], 0
	v_mfma_f32_16x16x32_bf16 v[12:15], v[128:131], v[202:205], 0
	v_mfma_f32_16x16x32_bf16 v[8:11], v[136:139], v[202:205], 0
	v_mfma_f32_16x16x32_bf16 v[60:63], v[132:135], v[182:185], v[60:63]
	v_mfma_f32_16x16x32_bf16 v[56:59], v[140:143], v[182:185], v[56:59]
	v_mfma_f32_16x16x32_bf16 v[44:47], v[132:135], v[190:193], v[44:47]
	v_mfma_f32_16x16x32_bf16 v[40:43], v[140:143], v[190:193], v[40:43]
	v_mfma_f32_16x16x32_bf16 v[28:31], v[132:135], v[198:201], v[28:31]
	v_mfma_f32_16x16x32_bf16 v[24:27], v[140:143], v[198:201], v[24:27]
	v_mfma_f32_16x16x32_bf16 v[12:15], v[132:135], v[212:215], v[12:15]
	v_mfma_f32_16x16x32_bf16 v[8:11], v[140:143], v[212:215], v[8:11]
	v_mfma_f32_16x16x32_bf16 v[52:55], v[154:157], v[178:181], 0
	v_mfma_f32_16x16x32_bf16 v[48:51], v[170:173], v[178:181], 0
	v_mfma_f32_16x16x32_bf16 v[36:39], v[154:157], v[186:189], 0
	v_mfma_f32_16x16x32_bf16 v[32:35], v[170:173], v[186:189], 0
	v_mfma_f32_16x16x32_bf16 v[20:23], v[154:157], v[194:197], 0
	v_mfma_f32_16x16x32_bf16 v[16:19], v[170:173], v[194:197], 0
	v_mfma_f32_16x16x32_bf16 v[4:7], v[154:157], v[202:205], 0
	v_mfma_f32_16x16x32_bf16 v[0:3], v[170:173], v[202:205], 0
	v_mfma_f32_16x16x32_bf16 v[52:55], v[158:161], v[182:185], v[52:55]
	v_mfma_f32_16x16x32_bf16 v[48:51], v[174:177], v[182:185], v[48:51]
	v_mfma_f32_16x16x32_bf16 v[36:39], v[158:161], v[190:193], v[36:39]
	v_mfma_f32_16x16x32_bf16 v[32:35], v[174:177], v[190:193], v[32:35]
	v_mfma_f32_16x16x32_bf16 v[20:23], v[158:161], v[198:201], v[20:23]
	v_mfma_f32_16x16x32_bf16 v[16:19], v[174:177], v[198:201], v[16:19]
	v_mfma_f32_16x16x32_bf16 v[4:7], v[158:161], v[212:215], v[4:7]
	v_mfma_f32_16x16x32_bf16 v[0:3], v[174:177], v[212:215], v[0:3]
	s_barrier
	s_branch .Lpeel_p9b

.Lpeel_p9b:
	s_add_i32 s43, 0, 0x18000
	s_add_i32 s44, 0, 0x1c000
	v_add_u32_e32 v140, s43, v163
	v_add_u32_e32 v174, s44, v163
	ds_read_b128 v[128:131], v140
	ds_read_b128 v[132:135], v140 offset:1024
	ds_read_b128 v[136:139], v140 offset:2048
	ds_read_b128 v[140:143], v140 offset:3072
	ds_read_b128 v[154:157], v174
	ds_read_b128 v[158:161], v174 offset:1024
	ds_read_b128 v[170:173], v174 offset:2048
	ds_read_b128 v[174:177], v174 offset:3072
	s_add_u32 s12, s18, 0xb0000
	s_addc_u32 s13, s19, 0
	s_mov_b32 m0, s23
	v_lshl_add_u64 v[222:223], s[12:13], 0, v[148:149]
	ds_read_b128 v[178:181], v165 offset:32768
	ds_read_b128 v[182:185], v165 offset:33792
	ds_read_b128 v[186:189], v165 offset:34816
	ds_read_b128 v[190:193], v165 offset:35840
	ds_read_b128 v[194:197], v165 offset:36864
	ds_read_b128 v[198:201], v165 offset:37888
	ds_read_b128 v[202:205], v165 offset:38912
	ds_read_b128 v[212:215], v165 offset:39936
	global_load_lds_dwordx4 v[222:223], off
	v_lshl_add_u64 v[222:223], s[12:13], 0, v[146:147]
	s_mov_b32 m0, s24
	s_nop 0
	global_load_lds_dwordx4 v[222:223], off
	s_waitcnt vmcnt(8)
	s_waitcnt lgkmcnt(0)
	s_barrier
	s_waitcnt lgkmcnt(0)
	v_mfma_f32_16x16x32_bf16 v[124:127], v[128:131], v[178:181], v[124:127]
	v_mfma_f32_16x16x32_bf16 v[120:123], v[136:139], v[178:181], v[120:123]
	v_mfma_f32_16x16x32_bf16 v[112:115], v[128:131], v[186:189], v[112:115]
	v_mfma_f32_16x16x32_bf16 v[104:107], v[136:139], v[186:189], v[104:107]
	v_mfma_f32_16x16x32_bf16 v[92:95], v[128:131], v[194:197], v[92:95]
	v_mfma_f32_16x16x32_bf16 v[88:91], v[136:139], v[194:197], v[88:91]
	v_mfma_f32_16x16x32_bf16 v[76:79], v[128:131], v[202:205], v[76:79]
	v_mfma_f32_16x16x32_bf16 v[72:75], v[136:139], v[202:205], v[72:75]
	v_mfma_f32_16x16x32_bf16 v[124:127], v[132:135], v[182:185], v[124:127]
	v_mfma_f32_16x16x32_bf16 v[120:123], v[140:143], v[182:185], v[120:123]
	v_mfma_f32_16x16x32_bf16 v[112:115], v[132:135], v[190:193], v[112:115]
	v_mfma_f32_16x16x32_bf16 v[104:107], v[140:143], v[190:193], v[104:107]
	v_mfma_f32_16x16x32_bf16 v[92:95], v[132:135], v[198:201], v[92:95]
	v_mfma_f32_16x16x32_bf16 v[88:91], v[140:143], v[198:201], v[88:91]
	v_mfma_f32_16x16x32_bf16 v[76:79], v[132:135], v[212:215], v[76:79]
	v_mfma_f32_16x16x32_bf16 v[72:75], v[140:143], v[212:215], v[72:75]
	v_mfma_f32_16x16x32_bf16 v[116:119], v[154:157], v[178:181], v[116:119]
	v_mfma_f32_16x16x32_bf16 v[108:111], v[170:173], v[178:181], v[108:111]
	v_mfma_f32_16x16x32_bf16 v[100:103], v[154:157], v[186:189], v[100:103]
	v_mfma_f32_16x16x32_bf16 v[96:99], v[170:173], v[186:189], v[96:99]
	v_mfma_f32_16x16x32_bf16 v[84:87], v[154:157], v[194:197], v[84:87]
	v_mfma_f32_16x16x32_bf16 v[80:83], v[170:173], v[194:197], v[80:83]
	v_mfma_f32_16x16x32_bf16 v[68:71], v[154:157], v[202:205], v[68:71]
	v_mfma_f32_16x16x32_bf16 v[64:67], v[170:173], v[202:205], v[64:67]
	v_mfma_f32_16x16x32_bf16 v[116:119], v[158:161], v[182:185], v[116:119]
	v_mfma_f32_16x16x32_bf16 v[108:111], v[174:177], v[182:185], v[108:111]
	v_mfma_f32_16x16x32_bf16 v[100:103], v[158:161], v[190:193], v[100:103]
	v_mfma_f32_16x16x32_bf16 v[96:99], v[174:177], v[190:193], v[96:99]
	v_mfma_f32_16x16x32_bf16 v[84:87], v[158:161], v[198:201], v[84:87]
	v_mfma_f32_16x16x32_bf16 v[80:83], v[174:177], v[198:201], v[80:83]
	v_mfma_f32_16x16x32_bf16 v[68:71], v[158:161], v[212:215], v[68:71]
	v_mfma_f32_16x16x32_bf16 v[64:67], v[174:177], v[212:215], v[64:67]
	s_barrier
	s_add_i32 s12, s43, s20
	v_lshl_add_u64 v[166:167], v[166:167], 0, s[74:75]
	s_mov_b32 m0, s12
	ds_read_b128 v[178:181], v165 offset:49152
	ds_read_b128 v[182:185], v165 offset:50176
	ds_read_b128 v[186:189], v165 offset:51200
	ds_read_b128 v[190:193], v165 offset:52224
	ds_read_b128 v[194:197], v165 offset:53248
	ds_read_b128 v[198:201], v165 offset:54272
	ds_read_b128 v[202:205], v165 offset:55296
	ds_read_b128 v[212:215], v165 offset:56320
	global_load_lds_dwordx4 v[166:167], off
	s_add_i32 m0, s12, 0x2000
	s_add_u32 s12, s16, 0xb0080
	v_lshl_add_u64 v[166:167], v[216:217], 0, s[74:75]
	s_addc_u32 s13, s17, 0
	s_add_i32 s16, s44, s20
	global_load_lds_dwordx4 v[166:167], off
	v_lshl_add_u64 v[166:167], s[12:13], 0, v[168:169]
	s_mov_b32 m0, s16
	s_nop 0
	global_load_lds_dwordx4 v[166:167], off
	v_lshl_add_u64 v[166:167], s[12:13], 0, v[144:145]
	s_add_i32 m0, s16, 0x2000
	s_nop 0
	global_load_lds_dwordx4 v[166:167], off
	v_lshl_add_u64 v[166:167], v[218:219], 0, s[74:75]
	s_mov_b32 m0, s31
	s_nop 0
	global_load_lds_dwordx4 v[166:167], off
	v_lshl_add_u64 v[166:167], v[220:221], 0, s[74:75]
	s_mov_b32 m0, s34
	s_nop 0
	global_load_lds_dwordx4 v[166:167], off
	s_waitcnt vmcnt(8)
	s_waitcnt lgkmcnt(0)
	s_barrier
	s_waitcnt lgkmcnt(0)
	v_mfma_f32_16x16x32_bf16 v[60:63], v[128:131], v[178:181], v[60:63]
	v_mfma_f32_16x16x32_bf16 v[56:59], v[136:139], v[178:181], v[56:59]
	v_mfma_f32_16x16x32_bf16 v[44:47], v[128:131], v[186:189], v[44:47]
	v_mfma_f32_16x16x32_bf16 v[40:43], v[136:139], v[186:189], v[40:43]
	v_mfma_f32_16x16x32_bf16 v[28:31], v[128:131], v[194:197], v[28:31]
	v_mfma_f32_16x16x32_bf16 v[24:27], v[136:139], v[194:197], v[24:27]
	v_mfma_f32_16x16x32_bf16 v[12:15], v[128:131], v[202:205], v[12:15]
	v_mfma_f32_16x16x32_bf16 v[8:11], v[136:139], v[202:205], v[8:11]
	v_mfma_f32_16x16x32_bf16 v[60:63], v[132:135], v[182:185], v[60:63]
	v_mfma_f32_16x16x32_bf16 v[56:59], v[140:143], v[182:185], v[56:59]
	v_mfma_f32_16x16x32_bf16 v[44:47], v[132:135], v[190:193], v[44:47]
	v_mfma_f32_16x16x32_bf16 v[40:43], v[140:143], v[190:193], v[40:43]
	v_mfma_f32_16x16x32_bf16 v[28:31], v[132:135], v[198:201], v[28:31]
	v_mfma_f32_16x16x32_bf16 v[24:27], v[140:143], v[198:201], v[24:27]
	v_mfma_f32_16x16x32_bf16 v[12:15], v[132:135], v[212:215], v[12:15]
	v_mfma_f32_16x16x32_bf16 v[8:11], v[140:143], v[212:215], v[8:11]
	v_mfma_f32_16x16x32_bf16 v[52:55], v[154:157], v[178:181], v[52:55]
	v_mfma_f32_16x16x32_bf16 v[48:51], v[170:173], v[178:181], v[48:51]
	v_mfma_f32_16x16x32_bf16 v[36:39], v[154:157], v[186:189], v[36:39]
	v_mfma_f32_16x16x32_bf16 v[32:35], v[170:173], v[186:189], v[32:35]
	v_mfma_f32_16x16x32_bf16 v[20:23], v[154:157], v[194:197], v[20:23]
	v_mfma_f32_16x16x32_bf16 v[16:19], v[170:173], v[194:197], v[16:19]
	v_mfma_f32_16x16x32_bf16 v[4:7], v[154:157], v[202:205], v[4:7]
	v_mfma_f32_16x16x32_bf16 v[0:3], v[170:173], v[202:205], v[0:3]
	v_mfma_f32_16x16x32_bf16 v[52:55], v[158:161], v[182:185], v[52:55]
	v_mfma_f32_16x16x32_bf16 v[48:51], v[174:177], v[182:185], v[48:51]
	v_mfma_f32_16x16x32_bf16 v[36:39], v[158:161], v[190:193], v[36:39]
	v_mfma_f32_16x16x32_bf16 v[32:35], v[174:177], v[190:193], v[32:35]
	v_mfma_f32_16x16x32_bf16 v[20:23], v[158:161], v[198:201], v[20:23]
	v_mfma_f32_16x16x32_bf16 v[16:19], v[174:177], v[198:201], v[16:19]
	v_mfma_f32_16x16x32_bf16 v[4:7], v[158:161], v[212:215], v[4:7]
	v_mfma_f32_16x16x32_bf16 v[0:3], v[174:177], v[212:215], v[0:3]
	s_barrier
	s_add_i32 s42, s42, 2
	s_add_u32 s40, s40, 0x100
	s_addc_u32 s41, s41, 0
	s_cmp_gt_u32 s42, 41
	s_mov_b64 s[12:13], s[14:15]
	s_cbranch_scc0 .LBB0_1032
	s_and_b64 vcc, exec, s[8:9]
	s_cbranch_vccz .LBB0_1035
	s_barrier
